# stack + norm2 row loads hoisted above the table build + up-epilogue conv-weight words requested at the epilogue head
# speedup vs baseline: 1.0045x; 1.0045x over previous
.LBB1_871:
	s_ashr_i32 s7, s1, 7
	s_mul_hi_i32 s9, s7, 0xc000
	s_mul_i32 s7, s7, 0xc000
	s_add_u32 s10, s5, s7
	s_addc_u32 s11, s6, s9
	s_waitcnt vmcnt(0)
	s_barrier
	v_lshl_add_u64 v[16:17], v[104:105], 2, s[10:11]
	global_load_dwordx4 v[4:7], v[110:111], off
	global_load_dwordx4 v[8:11], v[114:115], off
	global_load_dwordx4 v[0:3], v[106:107], off
	v_add_co_u32_e32 v12, vcc, s75, v16
	s_add_i32 s24, s18, 1
	s_nop 0
	v_addc_co_u32_e32 v13, vcc, 0, v17, vcc
	global_load_dwordx4 v[12:15], v[12:13], off
	s_nop 0
	global_load_dwordx4 v[16:19], v[16:17], off
	s_ashr_i32 s19, s18, 31
	s_ashr_i32 s25, s24, 31
	s_lshl_b64 s[10:11], s[18:19], 12
	s_lshl_b64 s[38:39], s[24:25], 12
	v_lshl_add_u64 v[20:21], v[108:109], 0, s[10:11]
	s_add_i32 s24, s18, 2
	s_add_i32 s30, s18, 3
	s_ashr_i32 s25, s24, 31
	s_ashr_i32 s31, s30, 31
	s_lshl_b64 s[26:27], s[24:25], 12
	s_lshl_b64 s[30:31], s[30:31], 12
	s_add_u32 s36, s29, s10
	s_mov_b32 s10, 0x358637bd
	s_addc_u32 s37, s8, s11
	v_lshl_add_u64 v[22:23], v[108:109], 0, s[38:39]
	v_lshl_add_u64 v[24:25], v[108:109], 0, s[26:27]
	v_lshl_add_u64 v[26:27], v[108:109], 0, s[30:31]
	global_load_dwordx4 v[116:119], v[20:21], off
	global_load_dwordx4 v[120:123], v[20:21], off offset:1024
	global_load_dwordx4 v[148:151], v[20:21], off offset:2048
	global_load_dwordx4 v[152:155], v[20:21], off offset:3072
	global_load_dwordx4 v[100:103], v[22:23], off
	global_load_dwordx4 v[96:99], v[22:23], off offset:1024
	global_load_dwordx4 v[92:95], v[22:23], off offset:2048
	global_load_dwordx4 v[88:91], v[22:23], off offset:3072
	global_load_dwordx4 v[84:87], v[24:25], off
	global_load_dwordx4 v[80:83], v[24:25], off offset:1024
	global_load_dwordx4 v[76:79], v[24:25], off offset:2048
	global_load_dwordx4 v[72:75], v[24:25], off offset:3072
	global_load_dwordx4 v[68:71], v[26:27], off
	global_load_dwordx4 v[64:67], v[26:27], off offset:1024
	global_load_dwordx4 v[60:63], v[26:27], off offset:2048
	global_load_dwordx4 v[56:59], v[26:27], off offset:3072
	s_waitcnt vmcnt(20)
	v_pk_add_f32 v[6:7], v[6:7], 1.0 op_sel_hi:[1,0]
	v_pk_add_f32 v[4:5], v[4:5], 1.0 op_sel_hi:[1,0]
	s_waitcnt vmcnt(18)
	v_pk_mul_f32 v[6:7], v[2:3], v[6:7]
	v_pk_mul_f32 v[4:5], v[0:1], v[4:5]
	ds_write_b128 v163, v[4:7] offset:16384
	ds_write_b128 v163, v[8:11] offset:24576
	s_waitcnt vmcnt(17)
	v_pk_add_f32 v[4:5], v[14:15], 1.0 op_sel_hi:[1,0]
	v_pk_add_f32 v[6:7], v[12:13], 1.0 op_sel_hi:[1,0]
	v_pk_mul_f32 v[2:3], v[2:3], v[4:5]
	v_pk_mul_f32 v[0:1], v[0:1], v[6:7]
	ds_write_b128 v163, v[0:3]
	s_waitcnt vmcnt(16)
	ds_write_b128 v163, v[16:19] offset:8192
	s_waitcnt lgkmcnt(0)
	s_barrier
	ds_read_b128 v[4:7], v112
	ds_read_b128 v[0:3], v112 offset:4096
	ds_read_b128 v[12:15], v112 offset:8192
	ds_read_b128 v[8:11], v112 offset:12288
	ds_read_b128 v[20:23], v160
	ds_read_b128 v[16:19], v160 offset:4096
	ds_read_b128 v[28:31], v160 offset:8192
	ds_read_b128 v[24:27], v160 offset:12288
	ds_read_b128 v[36:39], v161
	ds_read_b128 v[32:35], v161 offset:4096
	ds_read_b128 v[44:47], v161 offset:8192
	ds_read_b128 v[40:43], v161 offset:12288
	ds_read_b128 v[52:55], v162
	ds_read_b128 v[48:51], v162 offset:4096
	s_add_u32 s38, s29, s38
	s_addc_u32 s39, s8, s39
	s_add_u32 s26, s29, s26
	s_addc_u32 s27, s8, s27
	s_add_u32 s30, s29, s30
	s_addc_u32 s31, s8, s31
	s_waitcnt vmcnt(15)
	v_lshlrev_b32_e32 v142, 16, v117
	v_and_b32_e32 v143, 0xffff0000, v117
	v_lshlrev_b32_e32 v146, 16, v116
	v_and_b32_e32 v147, 0xffff0000, v116
	v_lshlrev_b32_e32 v144, 16, v118
	v_and_b32_e32 v145, 0xffff0000, v118
	v_pk_mul_f32 v[170:171], v[142:143], v[142:143]
	v_pk_mul_f32 v[172:173], v[146:147], v[146:147]
	v_lshlrev_b32_e32 v138, 16, v119
	v_and_b32_e32 v139, 0xffff0000, v119
	s_waitcnt vmcnt(14)
	v_lshlrev_b32_e32 v128, 16, v123
	v_and_b32_e32 v129, 0xffff0000, v123
	v_lshlrev_b32_e32 v136, 16, v122
	v_and_b32_e32 v137, 0xffff0000, v122
	s_waitcnt vmcnt(12)
	v_lshlrev_b32_e32 v122, 16, v153
	v_and_b32_e32 v123, 0xffff0000, v153
	v_lshlrev_b32_e32 v132, 16, v152
	v_and_b32_e32 v133, 0xffff0000, v152
	s_waitcnt vmcnt(11)
	v_lshlrev_b32_e32 v152, 16, v101
	v_and_b32_e32 v153, 0xffff0000, v101
	v_lshlrev_b32_e32 v156, 16, v100
	v_and_b32_e32 v157, 0xffff0000, v100
	s_waitcnt vmcnt(10)
	v_lshlrev_b32_e32 v100, 16, v99
	v_and_b32_e32 v101, 0xffff0000, v99
	v_pk_mul_f32 v[168:169], v[144:145], v[144:145]
	v_add_f32_e32 v99, v170, v171
	v_add_f32_e32 v170, v172, v173
	v_lshlrev_b32_e32 v134, 16, v121
	v_and_b32_e32 v135, 0xffff0000, v121
	v_lshlrev_b32_e32 v140, 16, v120
	v_and_b32_e32 v141, 0xffff0000, v120
	v_lshlrev_b32_e32 v116, 16, v155
	v_and_b32_e32 v117, 0xffff0000, v155
	v_lshlrev_b32_e32 v120, 16, v154
	v_and_b32_e32 v121, 0xffff0000, v154
	v_lshlrev_b32_e32 v154, 16, v97
	v_and_b32_e32 v155, 0xffff0000, v97
	v_lshlrev_b32_e32 v158, 16, v96
	v_and_b32_e32 v159, 0xffff0000, v96
	v_pk_mul_f32 v[96:97], v[138:139], v[138:139]
	v_add_f32_e32 v168, v168, v169
	v_add_f32_e32 v99, v170, v99
	v_pk_mul_f32 v[180:181], v[140:141], v[140:141]
	v_add_f32_e32 v96, v96, v97
	v_add_f32_e32 v99, v168, v99
	v_pk_mul_f32 v[178:179], v[134:135], v[134:135]
	v_add_f32_e32 v97, v180, v181
	v_add_f32_e32 v96, v96, v99
	v_pk_mul_f32 v[176:177], v[136:137], v[136:137]
	v_add_f32_e32 v169, v178, v179
	v_add_f32_e32 v96, v97, v96
	v_lshlrev_b32_e32 v130, 16, v148
	v_and_b32_e32 v131, 0xffff0000, v148
	v_pk_mul_f32 v[174:175], v[128:129], v[128:129]
	v_add_f32_e32 v171, v176, v177
	v_add_f32_e32 v96, v169, v96
	v_lshlrev_b32_e32 v124, 16, v149
	v_and_b32_e32 v125, 0xffff0000, v149
	v_pk_mul_f32 v[188:189], v[130:131], v[130:131]
	v_add_f32_e32 v172, v174, v175
	v_add_f32_e32 v96, v171, v96
	v_lshlrev_b32_e32 v126, 16, v150
	v_and_b32_e32 v127, 0xffff0000, v150
	v_pk_mul_f32 v[186:187], v[124:125], v[124:125]
	v_add_f32_e32 v173, v188, v189
	v_add_f32_e32 v96, v172, v96
	v_lshlrev_b32_e32 v118, 16, v151
	v_and_b32_e32 v119, 0xffff0000, v151
	v_pk_mul_f32 v[184:185], v[126:127], v[126:127]
	v_add_f32_e32 v174, v186, v187
	v_add_f32_e32 v96, v173, v96
	v_pk_mul_f32 v[182:183], v[118:119], v[118:119]
	v_add_f32_e32 v175, v184, v185
	v_add_f32_e32 v96, v174, v96
	v_pk_mul_f32 v[200:201], v[132:133], v[132:133]
	v_add_f32_e32 v176, v182, v183
	v_add_f32_e32 v96, v175, v96
	v_pk_mul_f32 v[198:199], v[122:123], v[122:123]
	v_add_f32_e32 v177, v200, v201
	v_add_f32_e32 v96, v176, v96
	v_pk_mul_f32 v[192:193], v[120:121], v[120:121]
	v_add_f32_e32 v178, v198, v199
	v_add_f32_e32 v96, v177, v96
	v_pk_mul_f32 v[190:191], v[116:117], v[116:117]
	v_add_f32_e32 v179, v192, v193
	v_add_f32_e32 v96, v178, v96
	v_add_f32_e32 v180, v190, v191
	v_add_f32_e32 v96, v179, v96
	v_add_f32_e32 v96, v180, v96
	v_lshlrev_b32_e32 v150, 16, v102
	v_and_b32_e32 v151, 0xffff0000, v102
	v_add_f32_dpp v96, v96, v96 quad_perm:[1,0,3,2] row_mask:0xf bank_mask:0xf bound_ctrl:1
	v_pk_mul_f32 v[210:211], v[152:153], v[152:153]
	v_pk_mul_f32 v[212:213], v[156:157], v[156:157]
	v_add_f32_dpp v96, v96, v96 quad_perm:[2,3,0,1] row_mask:0xf bank_mask:0xf bound_ctrl:1
	v_lshlrev_b32_e32 v148, 16, v103
	v_and_b32_e32 v149, 0xffff0000, v103
	v_add_f32_dpp v96, v96, v96 row_half_mirror row_mask:0xf bank_mask:0xf bound_ctrl:1
	v_pk_mul_f32 v[208:209], v[150:151], v[150:151]
	v_add_f32_e32 v168, v210, v211
	v_add_f32_dpp v96, v96, v96 row_mirror row_mask:0xf bank_mask:0xf bound_ctrl:1
	v_mov_b32_e32 v97, v96
	v_add_f32_e32 v192, v212, v213
	v_pk_mul_f32 v[206:207], v[148:149], v[148:149]
	v_permlane16_swap_b32_e32 v96, v97
	v_add_f32_e32 v168, v192, v168
	v_add_f32_e32 v192, v208, v209
	v_pk_mul_f32 v[240:241], v[158:159], v[158:159]
	v_add_f32_e32 v97, v96, v97
	v_add_f32_e32 v96, v206, v207
	v_add_f32_e32 v168, v192, v168
	v_lshlrev_b32_e32 v102, 16, v98
	v_and_b32_e32 v103, 0xffff0000, v98
	v_pk_mul_f32 v[238:239], v[154:155], v[154:155]
	v_add_f32_e32 v96, v96, v168
	v_add_f32_e32 v168, v240, v241
	v_pk_mul_f32 v[236:237], v[102:103], v[102:103]
	v_add_f32_e32 v96, v168, v96
	v_add_f32_e32 v168, v238, v239
	v_pk_mul_f32 v[234:235], v[100:101], v[100:101]
	s_waitcnt vmcnt(9)
	v_lshlrev_b32_e32 v178, 16, v92
	v_and_b32_e32 v179, 0xffff0000, v92
	v_add_f32_e32 v96, v168, v96
	v_add_f32_e32 v168, v236, v237
	v_lshlrev_b32_e32 v174, 16, v93
	v_and_b32_e32 v175, 0xffff0000, v93
	v_pk_mul_f32 v[92:93], v[178:179], v[178:179]
	v_add_f32_e32 v96, v168, v96
	v_add_f32_e32 v168, v234, v235
	v_lshlrev_b32_e32 v172, 16, v94
	v_and_b32_e32 v173, 0xffff0000, v94
	v_pk_mul_f32 v[176:177], v[174:175], v[174:175]
	v_add_f32_e32 v96, v168, v96
	v_add_f32_e32 v92, v92, v93
	v_lshlrev_b32_e32 v98, 16, v95
	v_and_b32_e32 v99, 0xffff0000, v95
	v_pk_mul_f32 v[94:95], v[172:173], v[172:173]
	v_add_f32_e32 v92, v92, v96
	v_add_f32_e32 v93, v176, v177
	v_pk_mul_f32 v[170:171], v[98:99], v[98:99]
	s_waitcnt vmcnt(8)
	v_lshlrev_b32_e32 v190, 16, v88
	v_and_b32_e32 v191, 0xffff0000, v88
	v_add_f32_e32 v92, v93, v92
	v_add_f32_e32 v93, v94, v95
	v_lshlrev_b32_e32 v186, 16, v89
	v_and_b32_e32 v187, 0xffff0000, v89
	v_pk_mul_f32 v[88:89], v[190:191], v[190:191]
	v_add_f32_e32 v92, v93, v92
	v_add_f32_e32 v93, v170, v171
	v_lshlrev_b32_e32 v184, 16, v90
	v_and_b32_e32 v185, 0xffff0000, v90
	v_pk_mul_f32 v[188:189], v[186:187], v[186:187]
	v_add_f32_e32 v92, v93, v92
	v_add_f32_e32 v88, v88, v89
	v_lshlrev_b32_e32 v180, 16, v91
	v_and_b32_e32 v181, 0xffff0000, v91
	v_pk_mul_f32 v[90:91], v[184:185], v[184:185]
	v_add_f32_e32 v88, v88, v92
	v_add_f32_e32 v89, v188, v189
	v_pk_mul_f32 v[182:183], v[180:181], v[180:181]
	v_add_f32_e32 v88, v89, v88
	v_add_f32_e32 v89, v90, v91
	v_add_f32_e32 v88, v89, v88
	v_add_f32_e32 v89, v182, v183
	v_add_f32_e32 v88, v89, v88
	v_mov_b32_e32 v169, v97
	s_nop 1
	v_permlane32_swap_b32_e32 v97, v169
	v_add_f32_dpp v88, v88, v88 quad_perm:[1,0,3,2] row_mask:0xf bank_mask:0xf bound_ctrl:1
	s_nop 1
	v_add_f32_dpp v88, v88, v88 quad_perm:[2,3,0,1] row_mask:0xf bank_mask:0xf bound_ctrl:1
	s_nop 1
	v_add_f32_dpp v88, v88, v88 row_half_mirror row_mask:0xf bank_mask:0xf bound_ctrl:1
	s_nop 1
	v_add_f32_dpp v88, v88, v88 row_mirror row_mask:0xf bank_mask:0xf bound_ctrl:1
	v_mov_b32_e32 v89, v88
	s_nop 1
	v_permlane16_swap_b32_e32 v88, v89
	v_add_f32_e32 v96, v88, v89
	v_mov_b32_e32 v168, v96
	s_nop 1
	v_permlane32_swap_b32_e32 v96, v168
	v_pk_add_f32 v[88:89], v[96:97], v[168:169]
	v_mov_b64_e32 v[96:97], s[10:11]
	s_mov_b32 s10, 0x3a000000
	v_pk_fma_f32 v[168:169], v[88:89], s[10:11], v[96:97] op_sel_hi:[1,0,0]
	s_nop 0
	v_mul_f32_e32 v88, 0x4b800000, v169
	v_cmp_gt_f32_e32 vcc, s69, v169
	s_nop 1
	v_cndmask_b32_e32 v88, v169, v88, vcc
	v_rsq_f32_e32 v169, v88
	ds_read_b128 v[92:95], v162 offset:8192
	ds_read_b128 v[88:91], v162 offset:12288
	v_mul_f32_e32 v170, 0x45800000, v169
	v_cndmask_b32_e32 v170, v169, v170, vcc
	v_pk_mul_f32 v[136:137], v[170:171], v[136:137] op_sel_hi:[0,1]
	v_pk_mul_f32 v[128:129], v[170:171], v[128:129] op_sel_hi:[0,1]
	s_waitcnt lgkmcnt(8)
	v_pk_fma_f32 v[136:137], v[16:17], v[136:137], v[24:25]
	v_pk_fma_f32 v[128:129], v[18:19], v[128:129], v[26:27]
	v_pk_mul_f32 v[126:127], v[170:171], v[126:127] op_sel_hi:[0,1]
	v_pk_mul_f32 v[118:119], v[170:171], v[118:119] op_sel_hi:[0,1]
	v_cvt_pk_bf16_f32 v136, v136, v137
	v_cvt_pk_bf16_f32 v137, v128, v129
	v_pk_mul_f32 v[128:129], v[170:171], v[130:131] op_sel_hi:[0,1]
	s_waitcnt lgkmcnt(4)
	v_pk_fma_f32 v[126:127], v[126:127], v[32:33], v[40:41]
	v_pk_mul_f32 v[124:125], v[170:171], v[124:125] op_sel_hi:[0,1]
	v_pk_fma_f32 v[118:119], v[118:119], v[34:35], v[42:43]
	v_pk_fma_f32 v[128:129], v[128:129], v[36:37], v[44:45]
	v_pk_fma_f32 v[130:131], v[124:125], v[38:39], v[46:47]
	v_cvt_pk_bf16_f32 v126, v126, v127
	v_cvt_pk_bf16_f32 v127, v118, v119
	v_pk_mul_f32 v[118:119], v[170:171], v[132:133] op_sel_hi:[0,1]
	v_cvt_pk_bf16_f32 v124, v128, v129
	v_cvt_pk_bf16_f32 v125, v130, v131
	s_waitcnt lgkmcnt(1)
	v_pk_fma_f32 v[118:119], v[118:119], v[52:53], v[92:93]
	v_pk_mul_f32 v[116:117], v[170:171], v[116:117] op_sel_hi:[0,1]
	global_store_dwordx4 v166, v[124:127], s[36:37]
	v_pk_mul_f32 v[122:123], v[170:171], v[122:123] op_sel_hi:[0,1]
	v_cmp_gt_f32_e32 vcc, s69, v168
	s_waitcnt lgkmcnt(0)
	v_pk_fma_f32 v[124:125], v[116:117], v[50:51], v[90:91]
	v_cvt_pk_bf16_f32 v116, v118, v119
	v_mul_f32_e32 v118, 0x4b800000, v168
	v_pk_fma_f32 v[122:123], v[122:123], v[54:55], v[94:95]
	v_cndmask_b32_e32 v118, v168, v118, vcc
	v_cvt_pk_bf16_f32 v117, v122, v123
	v_rsq_f32_e32 v122, v118
	v_pk_mul_f32 v[120:121], v[170:171], v[120:121] op_sel_hi:[0,1]
	v_pk_fma_f32 v[120:121], v[120:121], v[48:49], v[88:89]
	v_cvt_pk_bf16_f32 v119, v124, v125
	v_cvt_pk_bf16_f32 v118, v120, v121
	global_store_dwordx4 v167, v[116:119], s[36:37]
	v_pk_mul_f32 v[144:145], v[170:171], v[144:145] op_sel_hi:[0,1]
	v_pk_mul_f32 v[138:139], v[170:171], v[138:139] op_sel_hi:[0,1]
	v_mul_f32_e32 v116, 0x45800000, v122
	v_cndmask_b32_e32 v120, v122, v116, vcc
	v_pk_mul_f32 v[116:117], v[120:121], v[156:157] op_sel_hi:[0,1]
	v_pk_mul_f32 v[118:119], v[120:121], v[150:151] op_sel_hi:[0,1]
	v_pk_mul_f32 v[122:123], v[120:121], v[152:153] op_sel_hi:[0,1]
	v_pk_mul_f32 v[124:125], v[120:121], v[148:149] op_sel_hi:[0,1]
	v_pk_fma_f32 v[116:117], v[4:5], v[116:117], v[12:13]
	v_pk_fma_f32 v[118:119], v[0:1], v[118:119], v[8:9]
	v_pk_fma_f32 v[122:123], v[6:7], v[122:123], v[14:15]
	v_pk_fma_f32 v[124:125], v[2:3], v[124:125], v[10:11]
	v_cvt_pk_bf16_f32 v116, v116, v117
	v_cvt_pk_bf16_f32 v117, v122, v123
	v_cvt_pk_bf16_f32 v118, v118, v119
	v_cvt_pk_bf16_f32 v119, v124, v125
	global_store_dwordx4 v164, v[116:119], s[38:39]
	v_pk_mul_f32 v[102:103], v[120:121], v[102:103] op_sel_hi:[0,1]
	v_pk_mul_f32 v[100:101], v[120:121], v[100:101] op_sel_hi:[0,1]
	v_pk_mul_f32 v[116:117], v[120:121], v[158:159] op_sel_hi:[0,1]
	v_pk_mul_f32 v[118:119], v[120:121], v[154:155] op_sel_hi:[0,1]
	v_pk_fma_f32 v[116:117], v[20:21], v[116:117], v[28:29]
	v_pk_fma_f32 v[102:103], v[16:17], v[102:103], v[24:25]
	v_pk_fma_f32 v[118:119], v[22:23], v[118:119], v[30:31]
	v_pk_fma_f32 v[122:123], v[18:19], v[100:101], v[26:27]
	v_cvt_pk_bf16_f32 v100, v116, v117
	v_cvt_pk_bf16_f32 v101, v118, v119
	v_cvt_pk_bf16_f32 v102, v102, v103
	v_cvt_pk_bf16_f32 v103, v122, v123
	global_store_dwordx4 v165, v[100:103], s[38:39]
	v_pk_mul_f32 v[116:117], v[120:121], v[174:175] op_sel_hi:[0,1]
	v_pk_mul_f32 v[98:99], v[120:121], v[98:99] op_sel_hi:[0,1]
	v_pk_mul_f32 v[100:101], v[120:121], v[178:179] op_sel_hi:[0,1]
	v_pk_mul_f32 v[102:103], v[120:121], v[172:173] op_sel_hi:[0,1]
	v_pk_fma_f32 v[100:101], v[36:37], v[100:101], v[44:45]
	v_pk_fma_f32 v[102:103], v[32:33], v[102:103], v[40:41]
	v_pk_fma_f32 v[116:117], v[38:39], v[116:117], v[46:47]
	v_pk_fma_f32 v[118:119], v[34:35], v[98:99], v[42:43]
	v_cvt_pk_bf16_f32 v98, v100, v101
	v_cvt_pk_bf16_f32 v99, v116, v117
	v_cvt_pk_bf16_f32 v100, v102, v103
	v_cvt_pk_bf16_f32 v101, v118, v119
	global_store_dwordx4 v166, v[98:101], s[38:39]
	v_pk_mul_f32 v[102:103], v[120:121], v[186:187] op_sel_hi:[0,1]
	v_pk_mul_f32 v[116:117], v[120:121], v[180:181] op_sel_hi:[0,1]
	v_pk_mul_f32 v[98:99], v[120:121], v[190:191] op_sel_hi:[0,1]
	v_pk_mul_f32 v[100:101], v[120:121], v[184:185] op_sel_hi:[0,1]
	v_pk_fma_f32 v[98:99], v[52:53], v[98:99], v[92:93]
	v_pk_fma_f32 v[100:101], v[48:49], v[100:101], v[88:89]
	v_pk_fma_f32 v[102:103], v[54:55], v[102:103], v[94:95]
	v_pk_fma_f32 v[116:117], v[50:51], v[116:117], v[90:91]
	v_pk_fma_f32 v[144:145], v[0:1], v[144:145], v[8:9]
	v_pk_fma_f32 v[138:139], v[2:3], v[138:139], v[10:11]
	v_cvt_pk_bf16_f32 v98, v98, v99
	v_cvt_pk_bf16_f32 v99, v102, v103
	v_cvt_pk_bf16_f32 v100, v100, v101
	v_cvt_pk_bf16_f32 v101, v116, v117
	v_cvt_pk_bf16_f32 v144, v144, v145
	v_cvt_pk_bf16_f32 v145, v138, v139
	v_pk_mul_f32 v[138:139], v[170:171], v[140:141] op_sel_hi:[0,1]
	v_pk_mul_f32 v[134:135], v[170:171], v[134:135] op_sel_hi:[0,1]
	global_store_dwordx4 v167, v[98:101], s[38:39]
	s_waitcnt vmcnt(13)
	v_lshlrev_b32_e32 v102, 16, v85
	v_and_b32_e32 v103, 0xffff0000, v85
	v_lshlrev_b32_e32 v98, 16, v87
	v_and_b32_e32 v99, 0xffff0000, v87
	v_lshlrev_b32_e32 v126, 16, v84
	v_and_b32_e32 v127, 0xffff0000, v84
	v_pk_fma_f32 v[138:139], v[20:21], v[138:139], v[28:29]
	v_pk_fma_f32 v[140:141], v[22:23], v[134:135], v[30:31]
	v_pk_mul_f32 v[120:121], v[98:99], v[98:99]
	v_lshlrev_b32_e32 v100, 16, v86
	v_and_b32_e32 v101, 0xffff0000, v86
	v_pk_mul_f32 v[124:125], v[102:103], v[102:103]
	v_pk_mul_f32 v[128:129], v[126:127], v[126:127]
	v_cvt_pk_bf16_f32 v134, v138, v139
	v_cvt_pk_bf16_f32 v135, v140, v141
	v_pk_mul_f32 v[122:123], v[100:101], v[100:101]
	v_add_f32_e32 v120, v120, v121
	v_add_f32_e32 v121, v124, v125
	v_add_f32_e32 v124, v128, v129
	global_store_dwordx4 v165, v[134:137], s[36:37]
	v_add_f32_e32 v121, v124, v121
	v_add_f32_e32 v122, v122, v123
	s_waitcnt vmcnt(13)
	v_lshlrev_b32_e32 v136, 16, v80
	v_and_b32_e32 v137, 0xffff0000, v80
	v_lshlrev_b32_e32 v116, 16, v81
	v_and_b32_e32 v117, 0xffff0000, v81
	v_pk_mul_f32 v[138:139], v[136:137], v[136:137]
	v_add_f32_e32 v121, v122, v121
	v_pk_mul_f32 v[146:147], v[170:171], v[146:147] op_sel_hi:[0,1]
	v_lshlrev_b32_e32 v86, 16, v82
	v_and_b32_e32 v87, 0xffff0000, v82
	v_pk_mul_f32 v[134:135], v[116:117], v[116:117]
	v_add_f32_e32 v120, v120, v121
	v_add_f32_e32 v121, v138, v139
	v_pk_fma_f32 v[146:147], v[4:5], v[146:147], v[12:13]
	v_pk_mul_f32 v[142:143], v[170:171], v[142:143] op_sel_hi:[0,1]
	v_lshlrev_b32_e32 v84, 16, v83
	v_and_b32_e32 v85, 0xffff0000, v83
	v_pk_mul_f32 v[132:133], v[86:87], v[86:87]
	v_add_f32_e32 v120, v121, v120
	v_add_f32_e32 v121, v134, v135
	v_pk_fma_f32 v[176:177], v[6:7], v[142:143], v[14:15]
	v_cvt_pk_bf16_f32 v142, v146, v147
	v_pk_mul_f32 v[130:131], v[84:85], v[84:85]
	s_waitcnt vmcnt(12)
	v_lshlrev_b32_e32 v146, 16, v76
	v_and_b32_e32 v147, 0xffff0000, v76
	v_add_f32_e32 v120, v121, v120
	v_add_f32_e32 v121, v132, v133
	v_cvt_pk_bf16_f32 v143, v176, v177
	v_lshlrev_b32_e32 v118, 16, v77
	v_and_b32_e32 v119, 0xffff0000, v77
	v_pk_mul_f32 v[148:149], v[146:147], v[146:147]
	v_add_f32_e32 v120, v121, v120
	v_add_f32_e32 v121, v130, v131
	global_store_dwordx4 v164, v[142:145], s[36:37]
	v_lshlrev_b32_e32 v82, 16, v78
	v_and_b32_e32 v83, 0xffff0000, v78
	v_pk_mul_f32 v[144:145], v[118:119], v[118:119]
	v_add_f32_e32 v120, v121, v120
	v_add_f32_e32 v121, v148, v149
	v_lshlrev_b32_e32 v80, 16, v79
	v_and_b32_e32 v81, 0xffff0000, v79
	v_pk_mul_f32 v[142:143], v[82:83], v[82:83]
	v_add_f32_e32 v120, v121, v120
	v_add_f32_e32 v121, v144, v145
	v_pk_mul_f32 v[140:141], v[80:81], v[80:81]
	s_waitcnt vmcnt(12)
	v_lshlrev_b32_e32 v156, 16, v72
	v_and_b32_e32 v157, 0xffff0000, v72
	v_add_f32_e32 v120, v121, v120
	v_add_f32_e32 v121, v142, v143
	v_lshlrev_b32_e32 v152, 16, v73
	v_and_b32_e32 v153, 0xffff0000, v73
	v_pk_mul_f32 v[72:73], v[156:157], v[156:157]
	v_add_f32_e32 v120, v121, v120
	v_add_f32_e32 v121, v140, v141
	v_lshlrev_b32_e32 v78, 16, v74
	v_and_b32_e32 v79, 0xffff0000, v74
	v_pk_mul_f32 v[154:155], v[152:153], v[152:153]
	v_add_f32_e32 v120, v121, v120
	v_add_f32_e32 v72, v72, v73
	v_lshlrev_b32_e32 v76, 16, v75
	v_and_b32_e32 v77, 0xffff0000, v75
	v_pk_mul_f32 v[74:75], v[78:79], v[78:79]
	v_add_f32_e32 v72, v72, v120
	v_add_f32_e32 v73, v154, v155
	v_pk_mul_f32 v[150:151], v[76:77], v[76:77]
	v_add_f32_e32 v72, v73, v72
	v_add_f32_e32 v73, v74, v75
	v_add_f32_e32 v72, v73, v72
	v_add_f32_e32 v73, v150, v151
	v_add_f32_e32 v72, v73, v72
	s_waitcnt vmcnt(11)
	v_lshlrev_b32_e32 v128, 16, v69
	v_and_b32_e32 v129, 0xffff0000, v69
	v_add_f32_dpp v72, v72, v72 quad_perm:[1,0,3,2] row_mask:0xf bank_mask:0xf bound_ctrl:1
	v_lshlrev_b32_e32 v132, 16, v68
	v_and_b32_e32 v133, 0xffff0000, v68
	v_add_f32_dpp v72, v72, v72 quad_perm:[2,3,0,1] row_mask:0xf bank_mask:0xf bound_ctrl:1
	v_lshlrev_b32_e32 v124, 16, v70
	v_and_b32_e32 v125, 0xffff0000, v70
	v_add_f32_dpp v72, v72, v72 row_half_mirror row_mask:0xf bank_mask:0xf bound_ctrl:1
	v_pk_mul_f32 v[130:131], v[128:129], v[128:129]
	v_pk_mul_f32 v[68:69], v[132:133], v[132:133]
	v_add_f32_dpp v72, v72, v72 row_mirror row_mask:0xf bank_mask:0xf bound_ctrl:1
	v_mov_b32_e32 v73, v72
	v_lshlrev_b32_e32 v120, 16, v71
	v_and_b32_e32 v121, 0xffff0000, v71
	v_pk_mul_f32 v[70:71], v[124:125], v[124:125]
	v_add_f32_e32 v74, v130, v131
	v_add_f32_e32 v68, v68, v69
	v_permlane16_swap_b32_e32 v72, v73
	v_pk_mul_f32 v[122:123], v[120:121], v[120:121]
	s_waitcnt vmcnt(10)
	v_lshlrev_b32_e32 v148, 16, v64
	v_and_b32_e32 v149, 0xffff0000, v64
	v_add_f32_e32 v68, v68, v74
	v_add_f32_e32 v69, v70, v71
	v_add_f32_e32 v73, v72, v73
	v_lshlrev_b32_e32 v142, 16, v65
	v_and_b32_e32 v143, 0xffff0000, v65
	v_pk_mul_f32 v[64:65], v[148:149], v[148:149]
	v_add_f32_e32 v72, v122, v123
	v_add_f32_e32 v68, v69, v68
	v_lshlrev_b32_e32 v140, 16, v66
	v_and_b32_e32 v141, 0xffff0000, v66
	v_pk_mul_f32 v[144:145], v[142:143], v[142:143]
	v_add_f32_e32 v68, v72, v68
	v_add_f32_e32 v64, v64, v65
	v_lshlrev_b32_e32 v134, 16, v67
	v_and_b32_e32 v135, 0xffff0000, v67
	v_pk_mul_f32 v[66:67], v[140:141], v[140:141]
	v_add_f32_e32 v64, v64, v68
	v_add_f32_e32 v65, v144, v145
	v_pk_mul_f32 v[138:139], v[134:135], v[134:135]
	s_waitcnt vmcnt(9)
	v_lshlrev_b32_e32 v172, 16, v60
	v_and_b32_e32 v173, 0xffff0000, v60
	v_add_f32_e32 v64, v65, v64
	v_add_f32_e32 v65, v66, v67
	v_lshlrev_b32_e32 v168, 16, v61
	v_and_b32_e32 v169, 0xffff0000, v61
	v_pk_mul_f32 v[60:61], v[172:173], v[172:173]
	v_add_f32_e32 v64, v65, v64
	v_add_f32_e32 v65, v138, v139
	v_lshlrev_b32_e32 v158, 16, v62
	v_and_b32_e32 v159, 0xffff0000, v62
	v_pk_mul_f32 v[170:171], v[168:169], v[168:169]
	v_add_f32_e32 v64, v65, v64
	v_add_f32_e32 v60, v60, v61
	v_lshlrev_b32_e32 v150, 16, v63
	v_and_b32_e32 v151, 0xffff0000, v63
	v_pk_mul_f32 v[62:63], v[158:159], v[158:159]
	v_add_f32_e32 v60, v60, v64
	v_add_f32_e32 v61, v170, v171
	v_pk_mul_f32 v[154:155], v[150:151], v[150:151]
	s_waitcnt vmcnt(8)
	v_lshlrev_b32_e32 v184, 16, v56
	v_and_b32_e32 v185, 0xffff0000, v56
	v_add_f32_e32 v60, v61, v60
	v_add_f32_e32 v61, v62, v63
	v_lshlrev_b32_e32 v180, 16, v57
	v_and_b32_e32 v181, 0xffff0000, v57
	v_pk_mul_f32 v[56:57], v[184:185], v[184:185]
	v_add_f32_e32 v60, v61, v60
	v_add_f32_e32 v61, v154, v155
	v_lshlrev_b32_e32 v178, 16, v58
	v_and_b32_e32 v179, 0xffff0000, v58
	v_pk_mul_f32 v[182:183], v[180:181], v[180:181]
	v_add_f32_e32 v60, v61, v60
	v_add_f32_e32 v56, v56, v57
	v_lshlrev_b32_e32 v174, 16, v59
	v_and_b32_e32 v175, 0xffff0000, v59
	v_pk_mul_f32 v[58:59], v[178:179], v[178:179]
	v_add_f32_e32 v56, v56, v60
	v_add_f32_e32 v57, v182, v183
	v_pk_mul_f32 v[176:177], v[174:175], v[174:175]
	v_add_f32_e32 v56, v57, v56
	v_add_f32_e32 v57, v58, v59
	v_add_f32_e32 v56, v57, v56
	v_add_f32_e32 v57, v176, v177
	v_add_f32_e32 v56, v57, v56
	v_mov_b32_e32 v75, v73
	s_nop 1
	v_permlane32_swap_b32_e32 v73, v75
	v_add_f32_dpp v56, v56, v56 quad_perm:[1,0,3,2] row_mask:0xf bank_mask:0xf bound_ctrl:1
	s_nop 1
	v_add_f32_dpp v56, v56, v56 quad_perm:[2,3,0,1] row_mask:0xf bank_mask:0xf bound_ctrl:1
	s_nop 1
	v_add_f32_dpp v56, v56, v56 row_half_mirror row_mask:0xf bank_mask:0xf bound_ctrl:1
	s_nop 1
	v_add_f32_dpp v56, v56, v56 row_mirror row_mask:0xf bank_mask:0xf bound_ctrl:1
	v_mov_b32_e32 v57, v56
	s_nop 1
	v_permlane16_swap_b32_e32 v56, v57
	v_add_f32_e32 v72, v56, v57
	v_mov_b32_e32 v74, v72
	s_nop 1
	v_permlane32_swap_b32_e32 v72, v74
	v_pk_add_f32 v[56:57], v[72:73], v[74:75]
	s_nop 0
	v_pk_fma_f32 v[60:61], v[56:57], s[10:11], v[96:97] op_sel_hi:[1,0,0]
	s_nop 0
	v_mul_f32_e32 v56, 0x4b800000, v61
	v_cmp_gt_f32_e32 vcc, s69, v61
	s_nop 1
	v_cndmask_b32_e32 v56, v61, v56, vcc
	v_rsq_f32_e32 v56, v56
	v_mul_f32_e32 v61, 0x4b800000, v60
	v_mul_f32_e32 v57, 0x45800000, v56
	v_cndmask_b32_e32 v62, v56, v57, vcc
	v_pk_mul_f32 v[56:57], v[62:63], v[126:127] op_sel_hi:[0,1]
	v_pk_mul_f32 v[58:59], v[62:63], v[100:101] op_sel_hi:[0,1]
	v_pk_mul_f32 v[64:65], v[62:63], v[102:103] op_sel_hi:[0,1]
	v_pk_mul_f32 v[66:67], v[62:63], v[98:99] op_sel_hi:[0,1]
	v_pk_fma_f32 v[56:57], v[4:5], v[56:57], v[12:13]
	v_pk_fma_f32 v[58:59], v[0:1], v[58:59], v[8:9]
	v_pk_fma_f32 v[64:65], v[6:7], v[64:65], v[14:15]
	v_pk_fma_f32 v[66:67], v[2:3], v[66:67], v[10:11]
	v_cvt_pk_bf16_f32 v56, v56, v57
	v_cvt_pk_bf16_f32 v57, v64, v65
	v_cvt_pk_bf16_f32 v58, v58, v59
	v_cvt_pk_bf16_f32 v59, v66, v67
	global_store_dwordx4 v164, v[56:59], s[26:27]
	v_pk_mul_f32 v[64:65], v[62:63], v[116:117] op_sel_hi:[0,1]
	v_pk_mul_f32 v[66:67], v[62:63], v[84:85] op_sel_hi:[0,1]
	v_pk_mul_f32 v[56:57], v[62:63], v[136:137] op_sel_hi:[0,1]
	v_pk_mul_f32 v[58:59], v[62:63], v[86:87] op_sel_hi:[0,1]
	v_pk_fma_f32 v[56:57], v[20:21], v[56:57], v[28:29]
	v_pk_fma_f32 v[58:59], v[16:17], v[58:59], v[24:25]
	v_pk_fma_f32 v[64:65], v[22:23], v[64:65], v[30:31]
	v_pk_fma_f32 v[66:67], v[18:19], v[66:67], v[26:27]
	v_cvt_pk_bf16_f32 v56, v56, v57
	v_cvt_pk_bf16_f32 v57, v64, v65
	v_cvt_pk_bf16_f32 v58, v58, v59
	v_cvt_pk_bf16_f32 v59, v66, v67
	global_store_dwordx4 v165, v[56:59], s[26:27]
	v_pk_mul_f32 v[64:65], v[62:63], v[118:119] op_sel_hi:[0,1]
	v_pk_mul_f32 v[66:67], v[62:63], v[80:81] op_sel_hi:[0,1]
	v_pk_mul_f32 v[56:57], v[62:63], v[146:147] op_sel_hi:[0,1]
	v_pk_mul_f32 v[58:59], v[62:63], v[82:83] op_sel_hi:[0,1]
	v_cmp_gt_f32_e32 vcc, s69, v60
	v_pk_fma_f32 v[56:57], v[36:37], v[56:57], v[44:45]
	v_pk_fma_f32 v[58:59], v[32:33], v[58:59], v[40:41]
	v_pk_fma_f32 v[64:65], v[38:39], v[64:65], v[46:47]
	v_pk_fma_f32 v[66:67], v[34:35], v[66:67], v[42:43]
	v_cndmask_b32_e32 v60, v60, v61, vcc
	v_cvt_pk_bf16_f32 v56, v56, v57
	v_cvt_pk_bf16_f32 v57, v64, v65
	v_cvt_pk_bf16_f32 v58, v58, v59
	v_cvt_pk_bf16_f32 v59, v66, v67
	v_rsq_f32_e32 v60, v60
	global_store_dwordx4 v166, v[56:59], s[26:27]
	v_pk_mul_f32 v[64:65], v[62:63], v[152:153] op_sel_hi:[0,1]
	v_pk_fma_f32 v[64:65], v[54:55], v[64:65], v[94:95]
	v_pk_mul_f32 v[56:57], v[62:63], v[156:157] op_sel_hi:[0,1]
	v_pk_mul_f32 v[58:59], v[62:63], v[78:79] op_sel_hi:[0,1]
	v_pk_mul_f32 v[62:63], v[62:63], v[76:77] op_sel_hi:[0,1]
	v_pk_fma_f32 v[56:57], v[52:53], v[56:57], v[92:93]
	v_pk_fma_f32 v[58:59], v[48:49], v[58:59], v[88:89]
	v_pk_fma_f32 v[62:63], v[50:51], v[62:63], v[90:91]
	v_cvt_pk_bf16_f32 v56, v56, v57
	v_cvt_pk_bf16_f32 v57, v64, v65
	v_cvt_pk_bf16_f32 v58, v58, v59
	v_cvt_pk_bf16_f32 v59, v62, v63
	global_store_dwordx4 v167, v[56:59], s[26:27]
	s_nop 1
	v_mul_f32_e32 v56, 0x45800000, v60
	v_cndmask_b32_e32 v56, v60, v56, vcc
	v_pk_mul_f32 v[58:59], v[56:57], v[132:133] op_sel_hi:[0,1]
	v_pk_fma_f32 v[4:5], v[4:5], v[58:59], v[12:13]
	v_pk_mul_f32 v[12:13], v[56:57], v[124:125] op_sel_hi:[0,1]
	v_pk_fma_f32 v[8:9], v[0:1], v[12:13], v[8:9]
	v_pk_mul_f32 v[0:1], v[56:57], v[128:129] op_sel_hi:[0,1]
	v_pk_fma_f32 v[6:7], v[6:7], v[0:1], v[14:15]
	v_pk_mul_f32 v[0:1], v[56:57], v[120:121] op_sel_hi:[0,1]
	v_pk_fma_f32 v[10:11], v[2:3], v[0:1], v[10:11]
	v_cvt_pk_bf16_f32 v0, v4, v5
	v_cvt_pk_bf16_f32 v1, v6, v7
	v_cvt_pk_bf16_f32 v2, v8, v9
	v_cvt_pk_bf16_f32 v3, v10, v11
	global_store_dwordx4 v164, v[0:3], s[30:31]
	v_pk_mul_f32 v[4:5], v[56:57], v[142:143] op_sel_hi:[0,1]
	v_pk_mul_f32 v[6:7], v[56:57], v[134:135] op_sel_hi:[0,1]
	v_pk_mul_f32 v[0:1], v[56:57], v[148:149] op_sel_hi:[0,1]
	v_pk_mul_f32 v[2:3], v[56:57], v[140:141] op_sel_hi:[0,1]
	v_pk_fma_f32 v[0:1], v[20:21], v[0:1], v[28:29]
	v_pk_fma_f32 v[2:3], v[16:17], v[2:3], v[24:25]
	v_pk_fma_f32 v[4:5], v[22:23], v[4:5], v[30:31]
	v_pk_fma_f32 v[6:7], v[18:19], v[6:7], v[26:27]
	v_cvt_pk_bf16_f32 v0, v0, v1
	v_cvt_pk_bf16_f32 v1, v4, v5
	v_cvt_pk_bf16_f32 v2, v2, v3
	v_cvt_pk_bf16_f32 v3, v6, v7
	global_store_dwordx4 v165, v[0:3], s[30:31]
	v_pk_mul_f32 v[4:5], v[56:57], v[168:169] op_sel_hi:[0,1]
	v_pk_mul_f32 v[6:7], v[56:57], v[150:151] op_sel_hi:[0,1]
	v_pk_mul_f32 v[0:1], v[56:57], v[172:173] op_sel_hi:[0,1]
	v_pk_mul_f32 v[2:3], v[56:57], v[158:159] op_sel_hi:[0,1]
	v_pk_fma_f32 v[0:1], v[36:37], v[0:1], v[44:45]
	v_pk_fma_f32 v[2:3], v[32:33], v[2:3], v[40:41]
	v_pk_fma_f32 v[4:5], v[38:39], v[4:5], v[46:47]
	v_pk_fma_f32 v[6:7], v[34:35], v[6:7], v[42:43]
	v_cvt_pk_bf16_f32 v0, v0, v1
	v_cvt_pk_bf16_f32 v1, v4, v5
	v_cvt_pk_bf16_f32 v2, v2, v3
	v_cvt_pk_bf16_f32 v3, v6, v7
	global_store_dwordx4 v166, v[0:3], s[30:31]
	v_pk_mul_f32 v[4:5], v[56:57], v[180:181] op_sel_hi:[0,1]
	v_pk_mul_f32 v[6:7], v[56:57], v[174:175] op_sel_hi:[0,1]
	v_pk_mul_f32 v[0:1], v[56:57], v[184:185] op_sel_hi:[0,1]
	v_pk_mul_f32 v[2:3], v[56:57], v[178:179] op_sel_hi:[0,1]
	v_pk_fma_f32 v[0:1], v[52:53], v[0:1], v[92:93]
	v_pk_fma_f32 v[2:3], v[48:49], v[2:3], v[88:89]
	v_pk_fma_f32 v[4:5], v[54:55], v[4:5], v[94:95]
	v_pk_fma_f32 v[6:7], v[50:51], v[6:7], v[90:91]
	v_cvt_pk_bf16_f32 v0, v0, v1
	v_cvt_pk_bf16_f32 v1, v4, v5
	v_cvt_pk_bf16_f32 v2, v2, v3
	v_cvt_pk_bf16_f32 v3, v6, v7
	s_andn2_b64 vcc, exec, s[2:3]
	global_store_dwordx4 v167, v[0:3], s[30:31]
	s_cbranch_vccnz .LBB1_870
	s_ashr_i32 s17, s16, 31
	s_lshl_b64 s[10:11], s[16:17], 12
	v_lshl_add_u64 v[12:13], v[108:109], 0, s[10:11]
	global_load_dwordx4 v[0:3], v[12:13], off
	global_load_dwordx4 v[4:7], v[12:13], off offset:1024
	global_load_dwordx4 v[8:11], v[12:13], off offset:2048
	s_nop 0
	global_load_dwordx4 v[12:15], v[12:13], off offset:3072
	ds_read_b128 v[16:19], v112 offset:16384
	ds_read_b128 v[20:23], v112 offset:20480
	ds_read_b128 v[24:27], v112 offset:24576
	ds_read_b128 v[28:31], v112 offset:28672
	ds_read_b128 v[32:35], v160 offset:16384
	ds_read_b128 v[36:39], v160 offset:20480
	ds_read_b128 v[40:43], v160 offset:24576
	ds_read_b128 v[44:47], v160 offset:28672
	ds_read_b128 v[48:51], v161 offset:16384
	ds_read_b128 v[52:55], v161 offset:20480
	ds_read_b128 v[56:59], v161 offset:24576
	ds_read_b128 v[60:63], v161 offset:28672
	s_add_u32 s26, s29, s10
	s_addc_u32 s27, s8, s11
	s_waitcnt vmcnt(3)
	v_lshlrev_b32_e32 v68, 16, v1
	v_and_b32_e32 v69, 0xffff0000, v1
	v_lshlrev_b32_e32 v70, 16, v0
	v_and_b32_e32 v71, 0xffff0000, v0
	v_lshlrev_b32_e32 v66, 16, v2
	v_and_b32_e32 v67, 0xffff0000, v2
	s_waitcnt vmcnt(2)
	v_lshlrev_b32_e32 v72, 16, v7
	v_and_b32_e32 v73, 0xffff0000, v7
	v_lshlrev_b32_e32 v74, 16, v6
	v_and_b32_e32 v75, 0xffff0000, v6
	v_lshlrev_b32_e32 v76, 16, v5
	v_and_b32_e32 v77, 0xffff0000, v5
	v_lshlrev_b32_e32 v78, 16, v4
	v_and_b32_e32 v79, 0xffff0000, v4
	v_pk_mul_f32 v[4:5], v[68:69], v[68:69]
	v_pk_mul_f32 v[6:7], v[70:71], v[70:71]
	v_lshlrev_b32_e32 v64, 16, v3
	v_and_b32_e32 v65, 0xffff0000, v3
	v_pk_mul_f32 v[2:3], v[66:67], v[66:67]
	v_add_f32_e32 v4, v4, v5
	v_add_f32_e32 v5, v6, v7
	v_pk_mul_f32 v[0:1], v[64:65], v[64:65]
	v_add_f32_e32 v2, v2, v3
	v_add_f32_e32 v4, v5, v4
	s_waitcnt vmcnt(0)
	v_lshlrev_b32_e32 v88, 16, v15
	v_and_b32_e32 v89, 0xffff0000, v15
	v_lshlrev_b32_e32 v90, 16, v14
	v_and_b32_e32 v91, 0xffff0000, v14
	v_pk_mul_f32 v[14:15], v[78:79], v[78:79]
	v_add_f32_e32 v0, v0, v1
	v_add_f32_e32 v2, v2, v4
	v_lshlrev_b32_e32 v92, 16, v13
	v_and_b32_e32 v93, 0xffff0000, v13
	v_lshlrev_b32_e32 v94, 16, v12
	v_and_b32_e32 v95, 0xffff0000, v12
	v_pk_mul_f32 v[12:13], v[76:77], v[76:77]
	v_add_f32_e32 v1, v14, v15
	v_add_f32_e32 v0, v0, v2
	v_lshlrev_b32_e32 v80, 16, v11
	v_and_b32_e32 v81, 0xffff0000, v11
	v_lshlrev_b32_e32 v82, 16, v10
	v_and_b32_e32 v83, 0xffff0000, v10
	v_pk_mul_f32 v[10:11], v[74:75], v[74:75]
	v_add_f32_e32 v3, v12, v13
	v_add_f32_e32 v0, v1, v0
	v_lshlrev_b32_e32 v84, 16, v9
	v_and_b32_e32 v85, 0xffff0000, v9
	v_lshlrev_b32_e32 v86, 16, v8
	v_and_b32_e32 v87, 0xffff0000, v8
	v_pk_mul_f32 v[8:9], v[72:73], v[72:73]
	v_add_f32_e32 v6, v10, v11
	v_add_f32_e32 v0, v3, v0
	v_pk_mul_f32 v[102:103], v[86:87], v[86:87]
	v_add_f32_e32 v7, v8, v9
	v_add_f32_e32 v0, v6, v0
	v_pk_mul_f32 v[100:101], v[84:85], v[84:85]
	v_add_f32_e32 v8, v102, v103
	v_add_f32_e32 v0, v7, v0
	v_pk_mul_f32 v[98:99], v[82:83], v[82:83]
	v_add_f32_e32 v9, v100, v101
	v_add_f32_e32 v0, v8, v0
	v_pk_mul_f32 v[96:97], v[80:81], v[80:81]
	v_add_f32_e32 v10, v98, v99
	v_add_f32_e32 v0, v9, v0
	v_pk_mul_f32 v[122:123], v[94:95], v[94:95]
	v_add_f32_e32 v11, v96, v97
	v_add_f32_e32 v0, v10, v0
	v_pk_mul_f32 v[120:121], v[92:93], v[92:93]
	v_add_f32_e32 v12, v122, v123
	v_add_f32_e32 v0, v11, v0
	v_pk_mul_f32 v[118:119], v[90:91], v[90:91]
	v_add_f32_e32 v13, v120, v121
	v_add_f32_e32 v0, v12, v0
	v_pk_mul_f32 v[116:117], v[88:89], v[88:89]
	v_add_f32_e32 v14, v118, v119
	v_add_f32_e32 v0, v13, v0
	v_add_f32_e32 v15, v116, v117
	v_add_f32_e32 v0, v14, v0
	v_add_f32_e32 v0, v15, v0
	s_nop 1
	v_add_f32_dpp v0, v0, v0 quad_perm:[1,0,3,2] row_mask:0xf bank_mask:0xf bound_ctrl:1
	s_nop 1
	v_add_f32_dpp v0, v0, v0 quad_perm:[2,3,0,1] row_mask:0xf bank_mask:0xf bound_ctrl:1
	s_nop 1
	v_add_f32_dpp v0, v0, v0 row_half_mirror row_mask:0xf bank_mask:0xf bound_ctrl:1
	s_nop 1
	v_add_f32_dpp v0, v0, v0 row_mirror row_mask:0xf bank_mask:0xf bound_ctrl:1
	v_mov_b32_e32 v1, v0
	s_nop 1
	v_permlane16_swap_b32_e32 v0, v1
	v_add_f32_e32 v0, v0, v1
	v_mov_b32_e32 v1, v0
	s_nop 1
	v_permlane32_swap_b32_e32 v0, v1
	v_add_f32_e32 v0, v0, v1
	v_fmamk_f32 v0, v0, 0x3a000000, v214
	v_mul_f32_e32 v1, 0x4b800000, v0
	v_cmp_gt_f32_e32 vcc, s69, v0
	s_nop 1
	v_cndmask_b32_e32 v0, v0, v1, vcc
	v_rsq_f32_e32 v96, v0
	ds_read_b128 v[0:3], v162 offset:16384
	ds_read_b128 v[4:7], v162 offset:20480
	ds_read_b128 v[8:11], v162 offset:24576
	ds_read_b128 v[12:15], v162 offset:28672
	v_mul_f32_e32 v97, 0x45800000, v96
	v_cndmask_b32_e32 v96, v96, v97, vcc
	v_pk_mul_f32 v[70:71], v[96:97], v[70:71] op_sel_hi:[0,1]
	s_waitcnt lgkmcnt(13)
	v_pk_fma_f32 v[16:17], v[16:17], v[70:71], v[24:25]
	v_pk_mul_f32 v[24:25], v[96:97], v[66:67] op_sel_hi:[0,1]
	s_waitcnt lgkmcnt(12)
	v_pk_fma_f32 v[20:21], v[20:21], v[24:25], v[28:29]
	v_pk_mul_f32 v[24:25], v[96:97], v[68:69] op_sel_hi:[0,1]
	v_pk_fma_f32 v[18:19], v[18:19], v[24:25], v[26:27]
	v_pk_mul_f32 v[24:25], v[96:97], v[64:65] op_sel_hi:[0,1]
	v_pk_fma_f32 v[22:23], v[22:23], v[24:25], v[30:31]
	v_cvt_pk_bf16_f32 v16, v16, v17
	v_cvt_pk_bf16_f32 v17, v18, v19
	v_cvt_pk_bf16_f32 v18, v20, v21
	v_cvt_pk_bf16_f32 v19, v22, v23
	global_store_dwordx4 v164, v[16:19], s[26:27]
	v_pk_mul_f32 v[20:21], v[96:97], v[76:77] op_sel_hi:[0,1]
	v_pk_mul_f32 v[22:23], v[96:97], v[72:73] op_sel_hi:[0,1]
	v_pk_mul_f32 v[16:17], v[96:97], v[78:79] op_sel_hi:[0,1]
	v_pk_mul_f32 v[18:19], v[96:97], v[74:75] op_sel_hi:[0,1]
	s_waitcnt lgkmcnt(9)
	v_pk_fma_f32 v[16:17], v[32:33], v[16:17], v[40:41]
	s_waitcnt lgkmcnt(8)
	v_pk_fma_f32 v[18:19], v[36:37], v[18:19], v[44:45]
	v_pk_fma_f32 v[20:21], v[34:35], v[20:21], v[42:43]
	v_pk_fma_f32 v[22:23], v[38:39], v[22:23], v[46:47]
	v_cvt_pk_bf16_f32 v16, v16, v17
	v_cvt_pk_bf16_f32 v17, v20, v21
	v_cvt_pk_bf16_f32 v18, v18, v19
	v_cvt_pk_bf16_f32 v19, v22, v23
	global_store_dwordx4 v165, v[16:19], s[26:27]
	v_pk_mul_f32 v[20:21], v[96:97], v[84:85] op_sel_hi:[0,1]
	v_pk_mul_f32 v[22:23], v[96:97], v[80:81] op_sel_hi:[0,1]
	v_pk_mul_f32 v[16:17], v[96:97], v[86:87] op_sel_hi:[0,1]
	v_pk_mul_f32 v[18:19], v[96:97], v[82:83] op_sel_hi:[0,1]
	s_waitcnt lgkmcnt(5)
	v_pk_fma_f32 v[16:17], v[16:17], v[48:49], v[56:57]
	s_waitcnt lgkmcnt(4)
	v_pk_fma_f32 v[18:19], v[18:19], v[52:53], v[60:61]
	v_pk_fma_f32 v[20:21], v[20:21], v[50:51], v[58:59]
	v_pk_fma_f32 v[22:23], v[22:23], v[54:55], v[62:63]
	v_cvt_pk_bf16_f32 v16, v16, v17
	v_cvt_pk_bf16_f32 v17, v20, v21
	v_cvt_pk_bf16_f32 v18, v18, v19
	v_cvt_pk_bf16_f32 v19, v22, v23
	global_store_dwordx4 v166, v[16:19], s[26:27]
	s_nop 1
	v_pk_mul_f32 v[16:17], v[96:97], v[94:95] op_sel_hi:[0,1]
	s_waitcnt lgkmcnt(1)
	v_pk_fma_f32 v[0:1], v[16:17], v[0:1], v[8:9]
	v_pk_mul_f32 v[8:9], v[96:97], v[90:91] op_sel_hi:[0,1]
	s_waitcnt lgkmcnt(0)
	v_pk_fma_f32 v[4:5], v[8:9], v[4:5], v[12:13]
	v_pk_mul_f32 v[8:9], v[96:97], v[92:93] op_sel_hi:[0,1]
	v_pk_fma_f32 v[2:3], v[8:9], v[2:3], v[10:11]
	v_pk_mul_f32 v[8:9], v[96:97], v[88:89] op_sel_hi:[0,1]
	v_pk_fma_f32 v[6:7], v[8:9], v[6:7], v[14:15]
	v_cvt_pk_bf16_f32 v0, v0, v1
	v_cvt_pk_bf16_f32 v1, v2, v3
	v_cvt_pk_bf16_f32 v2, v4, v5
	v_cvt_pk_bf16_f32 v3, v6, v7
	global_store_dwordx4 v167, v[0:3], s[26:27]
	s_branch .LBB1_870

.LBB1_942:
	s_mov_b32 s19, -1
	s_mov_b64 s[38:39], 0
	v_mbcnt_lo_u32_b32 v112, s19, 0
	v_mbcnt_hi_u32_b32 v170, s19, v112
	v_add_u32_e32 v186, s54, v170
	v_and_b32_e32 v187, 0x80, v186
	v_cmp_eq_u32_e32 vcc, 0, v187
	s_lshl_b32 s42, s11, 7
	s_ashr_i32 s43, s42, 31
	v_cndmask_b32_e64 v188, v228, 0, vcc
	v_mov_b32_e32 v189, 0
	v_lshl_add_u64 v[188:189], s[78:79], 0, v[188:189]
	v_lshl_add_u64 v[188:189], s[42:43], 2, v[188:189]
	v_and_b32_e32 v190, 0x7f, v186
	v_lshlrev_b32_e32 v190, 2, v190
	v_mov_b32_e32 v191, 0
	v_lshl_add_u64 v[188:189], v[188:189], 0, v[190:191]
	v_lshrrev_b32_e32 v190, 8, v186
	v_mul_u32_u24_e32 v190, 0xb000, v190
	v_lshl_add_u64 v[190:191], v[188:189], 0, v[190:191]
	global_load_dword v192, v[190:191], off
	s_mov_b64 s[42:43], 0x16000
	v_lshl_add_u64 v[190:191], v[188:189], 0, s[42:43]
	v_cmp_gt_i32_e32 vcc, 0x100, v186
	s_and_saveexec_b64 s[42:43], vcc
	global_load_dword v193, v[190:191], off
	s_or_b64 exec, exec, s[42:43]
	v_lshrrev_b32_e32 v112, 1, v170
	v_and_b32_e32 v112, 56, v112
	v_and_b32_e32 v173, 15, v170
	v_add_u32_e32 v168, s66, v112
	v_cmp_lt_i32_e32 vcc, 14, v173
	s_and_saveexec_b64 s[26:27], vcc
	s_xor_b64 s[26:27], exec, s[26:27]
	s_mov_b64 s[38:39], exec
	s_or_saveexec_b64 s[26:27], s[26:27]
	v_mov_b64_e32 v[132:133], v[106:107]
	v_mov_b32_e32 v112, s68
	v_mov_b64_e32 v[130:131], v[104:105]
	s_xor_b64 exec, exec, s[26:27]
	v_cmp_eq_u32_e32 vcc, 0, v173
	s_andn2_b64 s[38:39], s[38:39], exec
	s_and_b64 s[40:41], vcc, exec
	v_mov_b64_e32 v[132:133], v[110:111]
	v_mov_b32_e32 v112, s90
	s_or_b64 s[38:39], s[38:39], s[40:41]
	v_mov_b64_e32 v[130:131], v[108:109]
	s_or_b64 exec, exec, s[26:27]
	s_and_saveexec_b64 s[26:27], s[38:39]
	s_cbranch_execz .LBB1_983
	v_lshl_add_u32 v112, v168, 2, v112
	ds_write_b128 v112, v[130:133]
	v_mov_b64_e32 v[132:133], v[78:79]
	v_cmp_gt_i32_e32 vcc, 15, v173
	s_mov_b64 s[40:41], -1
	v_mov_b32_e32 v134, 0x410
	v_mov_b64_e32 v[130:131], v[76:77]
	s_and_saveexec_b64 s[38:39], vcc
	s_cbranch_execz .LBB1_951
	v_cmp_eq_u32_e32 vcc, 0, v173
	s_mov_b64 s[40:41], 0
	v_mov_b32_e32 v134, 0x410
	s_and_saveexec_b64 s[42:43], vcc
	s_mov_b64 s[40:41], exec
	v_mov_b32_e32 v134, 16
	s_or_b64 exec, exec, s[42:43]
	v_mov_b64_e32 v[132:133], v[86:87]
	s_orn2_b64 s[40:41], s[40:41], exec
	v_mov_b64_e32 v[130:131], v[84:85]

.LBB1_983:
	s_or_b64 exec, exec, s[26:27]
	v_add_u32_e32 v169, s54, v170
	v_and_b32_e32 v112, 0x80, v169
	v_cmp_eq_u32_e32 vcc, 0, v112
	v_and_b32_e32 v130, 0x80, v169
	s_lshl_b32 s26, s11, 7
	v_cndmask_b32_e64 v112, v228, 0, vcc
	v_cmp_ne_u32_e64 s[38:39], 0, v130
	s_ashr_i32 s27, s26, 31
	v_and_b32_e32 v132, 0x7f, v169
	v_lshl_add_u64 v[130:131], s[78:79], 0, v[112:113]
	v_lshl_add_u64 v[130:131], s[26:27], 2, v[130:131]
	v_lshlrev_b32_e32 v112, 2, v132
	s_movk_i32 s11, 0x300
	v_lshl_add_u64 v[130:131], v[130:131], 0, v[112:113]
	v_cmp_gt_i32_e32 vcc, s11, v169
	s_and_saveexec_b64 s[40:41], vcc
	s_cbranch_execz .LBB1_985
	v_lshl_add_u32 v133, v169, 2, 0
	v_add_u32_e32 v133, 0x22400, v133
	s_waitcnt vmcnt(0)
	ds_write_b32 v133, v192
.LBB1_985:
	s_or_b64 exec, exec, s[40:41]
	s_movk_i32 s11, 0x100
	v_cmp_gt_i32_e32 vcc, s11, v169
	s_and_saveexec_b64 s[40:41], vcc
	s_cbranch_execz .LBB1_987
	v_add_u32_e32 v134, 0x200, v169
	v_lshl_add_u32 v131, v134, 2, 0
	v_add_u32_e32 v131, 0x22400, v131
	s_waitcnt vmcnt(0)
	ds_write_b32 v131, v193
